# speedup vs baseline: 1.0029x; 1.0029x over previous
.LBB0_551:
	v_mov_b64_e32 v[48:49], v[76:77]
	v_mov_b64_e32 v[40:41], v[72:73]
	v_mov_b64_e32 v[36:37], v[64:65]
	v_mov_b64_e32 v[44:45], v[68:69]
	s_andn2_b64 vcc, exec, s[60:61]
	v_mov_b64_e32 v[50:51], v[78:79]
	v_mov_b64_e32 v[42:43], v[74:75]
	v_mov_b64_e32 v[38:39], v[66:67]
	v_mov_b64_e32 v[46:47], v[70:71]
	s_cbranch_vccnz .LBB0_553
	v_add_u32_e32 v16, 0x20800, v118
	ds_read_b128 v[36:39], v16
	ds_read_b128 v[48:51], v16 offset:1024
	v_add_u32_e32 v16, s88, v125
	v_add_u32_e32 v16, 0xd000, v16
	ds_read_b64 v[40:41], v16 offset:0
	ds_read_b64 v[42:43], v16 offset:32
	ds_read_b64 v[44:45], v16 offset:0x900
	ds_read_b64 v[46:47], v16 offset:0x920
	ds_read_b64 v[52:53], v16 offset:0x1200
	ds_read_b64 v[54:55], v16 offset:0x1220
	ds_read_b64 v[56:57], v16 offset:0x1b00
	ds_read_b64 v[58:59], v16 offset:0x1b20
	ds_read_b64 v[128:129], v16 offset:64
	ds_read_b64 v[130:131], v16 offset:0x60
	ds_read_b64 v[132:133], v16 offset:0x940
	ds_read_b64 v[134:135], v16 offset:0x960
	ds_read_b64 v[136:137], v16 offset:0x1240
	ds_read_b64 v[138:139], v16 offset:0x1260
	ds_read_b64 v[140:141], v16 offset:0x1b40
	ds_read_b64 v[142:143], v16 offset:0x1b60
	v_ashrrev_i32_e32 v117, 31, v116
	s_waitcnt lgkmcnt(0)
	s_waitcnt lgkmcnt(0)
	v_lshlrev_b64 v[18:19], 11, v[116:117]
	s_waitcnt lgkmcnt(0)
	v_mfma_f32_16x16x32_bf16 v[40:43], v[40:43], v[36:39], v[64:67]
	v_lshl_add_u64 v[18:19], v[92:93], 0, v[18:19]
	s_mov_b32 s52, 0x9000
	v_mfma_f32_16x16x32_bf16 v[44:47], v[44:47], v[36:39], v[68:71]
	v_mfma_f32_16x16x32_bf16 v[52:55], v[52:55], v[36:39], v[72:75]
	v_mfma_f32_16x16x32_bf16 v[56:59], v[56:59], v[36:39], v[76:79]
	v_mfma_f32_16x16x32_bf16 v[36:39], v[128:131], v[48:51], v[40:43]
	s_nop 7
	global_store_dword v[18:19], v36, off sc1
	global_store_dword v[18:19], v37, off offset:2048 sc1
	v_mfma_f32_16x16x32_bf16 v[44:47], v[132:135], v[48:51], v[44:47]
	v_mfma_f32_16x16x32_bf16 v[40:43], v[136:139], v[48:51], v[52:55]
	s_nop 2
	v_add_co_u32_e32 v52, vcc, s68, v18
	v_mfma_f32_16x16x32_bf16 v[48:51], v[140:143], v[48:51], v[56:59]
	s_nop 0
	v_addc_co_u32_e32 v53, vcc, 0, v19, vcc
	global_store_dword v[52:53], v38, off sc1
	global_store_dword v[52:53], v39, off offset:2048 sc1
	v_add_co_u32_e32 v52, vcc, s47, v18
	s_nop 1
	v_addc_co_u32_e32 v53, vcc, 0, v19, vcc
	global_store_dword v[52:53], v44, off sc1
	global_store_dword v[52:53], v45, off offset:2048 sc1
	v_add_co_u32_e32 v52, vcc, s52, v18
	s_mov_b32 s52, 0x10000
	s_nop 0
	v_addc_co_u32_e32 v53, vcc, 0, v19, vcc
	global_store_dword v[52:53], v46, off sc1
	global_store_dword v[52:53], v47, off offset:2048 sc1
	v_add_co_u32_e32 v52, vcc, s52, v18
	s_nop 1
	v_addc_co_u32_e32 v53, vcc, 0, v19, vcc
	global_store_dword v[52:53], v40, off sc1
	global_store_dword v[52:53], v41, off offset:2048 sc1
	v_add_co_u32_e32 v52, vcc, 0x11000, v18
	s_nop 1
	v_addc_co_u32_e32 v53, vcc, 0, v19, vcc
	global_store_dword v[52:53], v42, off sc1
	global_store_dword v[52:53], v43, off offset:2048 sc1
	v_add_co_u32_e32 v52, vcc, 0x18000, v18
	s_nop 1
	v_addc_co_u32_e32 v53, vcc, 0, v19, vcc
	v_add_co_u32_e32 v18, vcc, 0x19000, v18
	global_store_dword v[52:53], v48, off sc1
	global_store_dword v[52:53], v49, off offset:2048 sc1
	v_addc_co_u32_e32 v19, vcc, 0, v19, vcc
	global_store_dword v[18:19], v50, off sc1
	global_store_dword v[18:19], v51, off offset:2048 sc1

.LBB0_566:
	s_waitcnt vmcnt(0)
	v_mov_b32_e32 v0, v228
	s_barrier
	s_nop 0
	v_cmp_eq_u32_e32 vcc, 0, v0
	s_and_saveexec_b64 s[8:9], vcc
	v_readlane_b32 s19, v255, 27
	s_cbranch_execz .LBB0_568
	v_readlane_b32 s4, v255, 18
	v_readlane_b32 s5, v255, 19
	s_and_b32 s2, s4, 7
	s_lshl_b32 s2, s2, 4
	s_lshr_b32 s4, s4, 3
	s_or_b32 s4, s4, s2
	s_ashr_i32 s4, s4, 3
	s_ashr_i32 s5, s4, 31
	s_lshl_b64 s[4:5], s[4:5], 2
	s_add_u32 s4, s19, s4
	v_readlane_b32 s2, v255, 26
	s_addc_u32 s5, s2, s5
	s_waitcnt vmcnt(0)
	v_mov_b64_e32 v[0:1], s[4:5]
	global_atomic_add v[0:1], v230, off
